# code placement: every GEMM K-loop head padded to byte 8 of a 64-byte line (the only placement of seven tried on the P8 loop that was not 1.7-3.5 % slower in a repeat-region probe); on top of the P4 sp
# baseline (speedup 1.0000x reference)
; template <class Epi, class Sched, bool ALIGN_EPI = false, bool SP2 = false, bool GRP = false>
; __device__ __forceinline__ void gemm_phase(PG8_LAS unsigned char* lds, const Gemm g, const Sched& S, const Epi& E) {
;     ...
;         for (int t = 0; t < nt; t += 2) {
;             const bool last = (t == nt - 2);
;             const char* a1 = cA + (size_t)(t + 1) * kstep;
;             const char* a2 = last ? nA : cA + (size_t)(t + 2) * kstep; const char* b2 = last ? nB : cB + (size_t)(t + 2) * kstep;
;             const char* a3 = a2 + kstep; const char* b3 = b2 + kstep;
;     ...
; #pragma unroll
;         for (int a = 0; a < 2; ++a)
; #pragma unroll
;             for (int b = 0; b < 2; ++b)
; #pragma unroll
;                 for (int m = 0; m < 4; ++m)
; #pragma unroll
;                     for (int n = 0; n < 2; ++n) acc[a][b][m][n] = (f32x4){0.f, 0.f, 0.f, 0.f};
;         cur = nxt; cA = nA; cB = nB; ++ui;
.LBB0_273:
	v_mov_b32_e32 v125, 0
	s_andn2_b64 vcc, exec, s[22:23]
	v_mov_b32_e32 v124, v125
	v_mov_b32_e32 v123, v125
	v_mov_b32_e32 v122, v125
	v_mov_b32_e32 v129, v125
	v_mov_b32_e32 v128, v125
	v_mov_b32_e32 v127, v125
	v_mov_b32_e32 v126, v125
	v_mov_b32_e32 v113, v125
	v_mov_b32_e32 v112, v125
	v_mov_b32_e32 v111, v125
	v_mov_b32_e32 v110, v125
	v_mov_b32_e32 v109, v125
	v_mov_b32_e32 v108, v125
	v_mov_b32_e32 v107, v125
	v_mov_b32_e32 v106, v125
	v_mov_b32_e32 v97, v125
	v_mov_b32_e32 v96, v125
	v_mov_b32_e32 v95, v125
	v_mov_b32_e32 v94, v125
	v_mov_b32_e32 v93, v125
	v_mov_b32_e32 v92, v125
	v_mov_b32_e32 v91, v125
	v_mov_b32_e32 v90, v125
	v_mov_b32_e32 v81, v125
	v_mov_b32_e32 v80, v125
	v_mov_b32_e32 v79, v125
	v_mov_b32_e32 v78, v125
	v_mov_b32_e32 v77, v125
	v_mov_b32_e32 v76, v125
	v_mov_b32_e32 v75, v125
	v_mov_b32_e32 v74, v125
	v_mov_b32_e32 v121, v125
	v_mov_b32_e32 v120, v125
	v_mov_b32_e32 v119, v125
	v_mov_b32_e32 v118, v125
	v_mov_b32_e32 v117, v125
	v_mov_b32_e32 v116, v125
	v_mov_b32_e32 v115, v125
	v_mov_b32_e32 v114, v125
	v_mov_b32_e32 v105, v125
	v_mov_b32_e32 v104, v125
	v_mov_b32_e32 v103, v125
	v_mov_b32_e32 v102, v125
	v_mov_b32_e32 v101, v125
	v_mov_b32_e32 v100, v125
	v_mov_b32_e32 v99, v125
	v_mov_b32_e32 v98, v125
	v_mov_b32_e32 v89, v125
	v_mov_b32_e32 v88, v125
	v_mov_b32_e32 v87, v125
	v_mov_b32_e32 v86, v125
	v_mov_b32_e32 v85, v125
	v_mov_b32_e32 v84, v125
	v_mov_b32_e32 v83, v125
	v_mov_b32_e32 v82, v125
	v_mov_b32_e32 v73, v125
	v_mov_b32_e32 v72, v125
	v_mov_b32_e32 v71, v125
	v_mov_b32_e32 v70, v125
	v_mov_b32_e32 v69, v125
	v_mov_b32_e32 v68, v125
	v_mov_b32_e32 v67, v125
	v_mov_b32_e32 v66, v125
	v_mov_b32_e32 v65, v125
	v_mov_b32_e32 v64, v125
	v_mov_b32_e32 v63, v125
	v_mov_b32_e32 v62, v125
	v_mov_b32_e32 v61, v125
	v_mov_b32_e32 v60, v125
	v_mov_b32_e32 v59, v125
	v_mov_b32_e32 v58, v125
	v_mov_b32_e32 v49, v125
	v_mov_b32_e32 v48, v125
	v_mov_b32_e32 v47, v125
	v_mov_b32_e32 v46, v125
	v_mov_b32_e32 v45, v125
	v_mov_b32_e32 v44, v125
	v_mov_b32_e32 v43, v125
	v_mov_b32_e32 v42, v125
	v_mov_b32_e32 v33, v125
	v_mov_b32_e32 v32, v125
	v_mov_b32_e32 v31, v125
	v_mov_b32_e32 v30, v125
	v_mov_b32_e32 v29, v125
	v_mov_b32_e32 v28, v125
	v_mov_b32_e32 v27, v125
	v_mov_b32_e32 v26, v125
	v_mov_b32_e32 v17, v125
	v_mov_b32_e32 v16, v125
	v_mov_b32_e32 v15, v125
	v_mov_b32_e32 v14, v125
	v_mov_b32_e32 v13, v125
	v_mov_b32_e32 v12, v125
	v_mov_b32_e32 v11, v125
	v_mov_b32_e32 v10, v125
	v_mov_b32_e32 v57, v125
	v_mov_b32_e32 v56, v125
	v_mov_b32_e32 v55, v125
	v_mov_b32_e32 v54, v125
	v_mov_b32_e32 v53, v125
	v_mov_b32_e32 v52, v125
	v_mov_b32_e32 v51, v125
	v_mov_b32_e32 v50, v125
	v_mov_b32_e32 v41, v125
	v_mov_b32_e32 v40, v125
	v_mov_b32_e32 v39, v125
	v_mov_b32_e32 v38, v125
	v_mov_b32_e32 v37, v125
	v_mov_b32_e32 v36, v125
	v_mov_b32_e32 v35, v125
	v_mov_b32_e32 v34, v125
	v_mov_b32_e32 v25, v125
	v_mov_b32_e32 v24, v125
	v_mov_b32_e32 v23, v125
	v_mov_b32_e32 v22, v125
	v_mov_b32_e32 v21, v125
	v_mov_b32_e32 v20, v125
	v_mov_b32_e32 v19, v125
	v_mov_b32_e32 v18, v125
	v_mov_b32_e32 v9, v125
	v_mov_b32_e32 v8, v125
	v_mov_b32_e32 v7, v125
	v_mov_b32_e32 v6, v125
	v_mov_b32_e32 v5, v125
	v_mov_b32_e32 v4, v125
	v_mov_b32_e32 v3, v125
	v_mov_b32_e32 v2, v125
	s_cbranch_vccnz .LBB0_276
	s_add_u32 s64, s64, 0x80
	s_addc_u32 s65, s65, 0
	s_add_u32 s40, s70, 0x100
	v_mov_b32_e32 v2, 0
	s_addc_u32 s41, s71, 0
	s_mov_b32 s3, 0
	v_mov_b32_e32 v3, v2
	v_mov_b32_e32 v4, v2
	v_mov_b32_e32 v5, v2
	v_mov_b32_e32 v6, v2
	v_mov_b32_e32 v7, v2
	v_mov_b32_e32 v8, v2
	v_mov_b32_e32 v9, v2
	v_mov_b32_e32 v18, v2
	v_mov_b32_e32 v19, v2
	v_mov_b32_e32 v20, v2
	v_mov_b32_e32 v21, v2
	v_mov_b32_e32 v22, v2
	v_mov_b32_e32 v23, v2
	v_mov_b32_e32 v24, v2
	v_mov_b32_e32 v25, v2
	v_mov_b32_e32 v34, v2
	v_mov_b32_e32 v35, v2
	v_mov_b32_e32 v36, v2
	v_mov_b32_e32 v37, v2
	v_mov_b32_e32 v38, v2
	v_mov_b32_e32 v39, v2
	v_mov_b32_e32 v40, v2
	v_mov_b32_e32 v41, v2
	v_mov_b32_e32 v50, v2
	v_mov_b32_e32 v51, v2
	v_mov_b32_e32 v52, v2
	v_mov_b32_e32 v53, v2
	v_mov_b32_e32 v54, v2
	v_mov_b32_e32 v55, v2
	v_mov_b32_e32 v56, v2
	v_mov_b32_e32 v57, v2
	v_mov_b32_e32 v10, v2
	v_mov_b32_e32 v11, v2
	v_mov_b32_e32 v12, v2
	v_mov_b32_e32 v13, v2
	v_mov_b32_e32 v14, v2
	v_mov_b32_e32 v15, v2
	v_mov_b32_e32 v16, v2
	v_mov_b32_e32 v17, v2
	v_mov_b32_e32 v26, v2
	v_mov_b32_e32 v27, v2
	v_mov_b32_e32 v28, v2
	v_mov_b32_e32 v29, v2
	v_mov_b32_e32 v30, v2
	v_mov_b32_e32 v31, v2
	v_mov_b32_e32 v32, v2
	v_mov_b32_e32 v33, v2
	v_mov_b32_e32 v42, v2
	v_mov_b32_e32 v43, v2
	v_mov_b32_e32 v44, v2
	v_mov_b32_e32 v45, v2
	v_mov_b32_e32 v46, v2
	v_mov_b32_e32 v47, v2
	v_mov_b32_e32 v48, v2
	v_mov_b32_e32 v49, v2
	v_mov_b32_e32 v58, v2
	v_mov_b32_e32 v59, v2
	v_mov_b32_e32 v60, v2
	v_mov_b32_e32 v61, v2
	v_mov_b32_e32 v62, v2
	v_mov_b32_e32 v63, v2
	v_mov_b32_e32 v64, v2
	v_mov_b32_e32 v65, v2
	v_mov_b32_e32 v66, v2
	v_mov_b32_e32 v67, v2
	v_mov_b32_e32 v68, v2
	v_mov_b32_e32 v69, v2
	v_mov_b32_e32 v70, v2
	v_mov_b32_e32 v71, v2
	v_mov_b32_e32 v72, v2
	v_mov_b32_e32 v73, v2
	v_mov_b32_e32 v82, v2
	v_mov_b32_e32 v83, v2
	v_mov_b32_e32 v84, v2
	v_mov_b32_e32 v85, v2
	v_mov_b32_e32 v86, v2
	v_mov_b32_e32 v87, v2
	v_mov_b32_e32 v88, v2
	v_mov_b32_e32 v89, v2
	v_mov_b32_e32 v98, v2
	v_mov_b32_e32 v99, v2
	v_mov_b32_e32 v100, v2
	v_mov_b32_e32 v101, v2
	v_mov_b32_e32 v102, v2
	v_mov_b32_e32 v103, v2
	v_mov_b32_e32 v104, v2
	v_mov_b32_e32 v105, v2
	v_mov_b32_e32 v114, v2
	v_mov_b32_e32 v115, v2
	v_mov_b32_e32 v116, v2
	v_mov_b32_e32 v117, v2
	v_mov_b32_e32 v118, v2
	v_mov_b32_e32 v119, v2
	v_mov_b32_e32 v120, v2
	v_mov_b32_e32 v121, v2
	v_mov_b32_e32 v74, v2
	v_mov_b32_e32 v75, v2
	v_mov_b32_e32 v76, v2
	v_mov_b32_e32 v77, v2
	v_mov_b32_e32 v78, v2
	v_mov_b32_e32 v79, v2
	v_mov_b32_e32 v80, v2
	v_mov_b32_e32 v81, v2
	v_mov_b32_e32 v90, v2
	v_mov_b32_e32 v91, v2
	v_mov_b32_e32 v92, v2
	v_mov_b32_e32 v93, v2
	v_mov_b32_e32 v94, v2
	v_mov_b32_e32 v95, v2
	v_mov_b32_e32 v96, v2
	v_mov_b32_e32 v97, v2
	v_mov_b32_e32 v106, v2
	v_mov_b32_e32 v107, v2
	v_mov_b32_e32 v108, v2
	v_mov_b32_e32 v109, v2
	v_mov_b32_e32 v110, v2
	v_mov_b32_e32 v111, v2
	v_mov_b32_e32 v112, v2
	v_mov_b32_e32 v113, v2
	v_mov_b32_e32 v126, v2
	v_mov_b32_e32 v127, v2
	v_mov_b32_e32 v128, v2
	v_mov_b32_e32 v129, v2
	v_mov_b32_e32 v122, v2
	v_mov_b32_e32 v123, v2
	v_mov_b32_e32 v124, v2
	v_mov_b32_e32 v125, v2
	s_nop 0
	s_nop 0
	s_nop 0
	s_nop 0
	s_nop 0
	s_nop 0

; template <class Epi, class Sched, bool ALIGN_EPI = false, bool SP2 = false, bool GRP = false>
; __device__ __forceinline__ void gemm_phase(PG8_LAS unsigned char* lds, const Gemm g, const Sched& S, const Epi& E) {
;     ...
;         for (int t = 0; t < nt; t += 2) {
;             const bool last = (t == nt - 2);
;             const char* a1 = cA + (size_t)(t + 1) * kstep;
;             const char* a2 = last ? nA : cA + (size_t)(t + 2) * kstep; const char* b2 = last ? nB : cB + (size_t)(t + 2) * kstep;
;             const char* a3 = a2 + kstep; const char* b3 = b2 + kstep;
;     ...
; #pragma unroll
;         for (int a = 0; a < 2; ++a)
; #pragma unroll
;             for (int b = 0; b < 2; ++b)
; #pragma unroll
;                 for (int m = 0; m < 4; ++m)
; #pragma unroll
;                     for (int n = 0; n < 2; ++n) acc[a][b][m][n] = (f32x4){0.f, 0.f, 0.f, 0.f};
;         cur = nxt; cA = nA; cB = nB; ++ui;
.LBB0_296:
	v_mov_b32_e32 v125, 0
	s_andn2_b64 vcc, exec, s[18:19]
	v_mov_b32_e32 v124, v125
	v_mov_b32_e32 v123, v125
	v_mov_b32_e32 v122, v125
	v_mov_b32_e32 v129, v125
	v_mov_b32_e32 v128, v125
	v_mov_b32_e32 v127, v125
	v_mov_b32_e32 v126, v125
	v_mov_b32_e32 v113, v125
	v_mov_b32_e32 v112, v125
	v_mov_b32_e32 v111, v125
	v_mov_b32_e32 v110, v125
	v_mov_b32_e32 v109, v125
	v_mov_b32_e32 v108, v125
	v_mov_b32_e32 v107, v125
	v_mov_b32_e32 v106, v125
	v_mov_b32_e32 v97, v125
	v_mov_b32_e32 v96, v125
	v_mov_b32_e32 v95, v125
	v_mov_b32_e32 v94, v125
	v_mov_b32_e32 v93, v125
	v_mov_b32_e32 v92, v125
	v_mov_b32_e32 v91, v125
	v_mov_b32_e32 v90, v125
	v_mov_b32_e32 v81, v125
	v_mov_b32_e32 v80, v125
	v_mov_b32_e32 v79, v125
	v_mov_b32_e32 v78, v125
	v_mov_b32_e32 v77, v125
	v_mov_b32_e32 v76, v125
	v_mov_b32_e32 v75, v125
	v_mov_b32_e32 v74, v125
	v_mov_b32_e32 v121, v125
	v_mov_b32_e32 v120, v125
	v_mov_b32_e32 v119, v125
	v_mov_b32_e32 v118, v125
	v_mov_b32_e32 v117, v125
	v_mov_b32_e32 v116, v125
	v_mov_b32_e32 v115, v125
	v_mov_b32_e32 v114, v125
	v_mov_b32_e32 v105, v125
	v_mov_b32_e32 v104, v125
	v_mov_b32_e32 v103, v125
	v_mov_b32_e32 v102, v125
	v_mov_b32_e32 v101, v125
	v_mov_b32_e32 v100, v125
	v_mov_b32_e32 v99, v125
	v_mov_b32_e32 v98, v125
	v_mov_b32_e32 v89, v125
	v_mov_b32_e32 v88, v125
	v_mov_b32_e32 v87, v125
	v_mov_b32_e32 v86, v125
	v_mov_b32_e32 v85, v125
	v_mov_b32_e32 v84, v125
	v_mov_b32_e32 v83, v125
	v_mov_b32_e32 v82, v125
	v_mov_b32_e32 v73, v125
	v_mov_b32_e32 v72, v125
	v_mov_b32_e32 v71, v125
	v_mov_b32_e32 v70, v125
	v_mov_b32_e32 v69, v125
	v_mov_b32_e32 v68, v125
	v_mov_b32_e32 v67, v125
	v_mov_b32_e32 v66, v125
	v_mov_b32_e32 v65, v125
	v_mov_b32_e32 v64, v125
	v_mov_b32_e32 v63, v125
	v_mov_b32_e32 v62, v125
	v_mov_b32_e32 v61, v125
	v_mov_b32_e32 v60, v125
	v_mov_b32_e32 v59, v125
	v_mov_b32_e32 v58, v125
	v_mov_b32_e32 v49, v125
	v_mov_b32_e32 v48, v125
	v_mov_b32_e32 v47, v125
	v_mov_b32_e32 v46, v125
	v_mov_b32_e32 v45, v125
	v_mov_b32_e32 v44, v125
	v_mov_b32_e32 v43, v125
	v_mov_b32_e32 v42, v125
	v_mov_b32_e32 v33, v125
	v_mov_b32_e32 v32, v125
	v_mov_b32_e32 v31, v125
	v_mov_b32_e32 v30, v125
	v_mov_b32_e32 v29, v125
	v_mov_b32_e32 v28, v125
	v_mov_b32_e32 v27, v125
	v_mov_b32_e32 v26, v125
	v_mov_b32_e32 v17, v125
	v_mov_b32_e32 v16, v125
	v_mov_b32_e32 v15, v125
	v_mov_b32_e32 v14, v125
	v_mov_b32_e32 v13, v125
	v_mov_b32_e32 v12, v125
	v_mov_b32_e32 v11, v125
	v_mov_b32_e32 v10, v125
	v_mov_b32_e32 v57, v125
	v_mov_b32_e32 v56, v125
	v_mov_b32_e32 v55, v125
	v_mov_b32_e32 v54, v125
	v_mov_b32_e32 v53, v125
	v_mov_b32_e32 v52, v125
	v_mov_b32_e32 v51, v125
	v_mov_b32_e32 v50, v125
	v_mov_b32_e32 v41, v125
	v_mov_b32_e32 v40, v125
	v_mov_b32_e32 v39, v125
	v_mov_b32_e32 v38, v125
	v_mov_b32_e32 v37, v125
	v_mov_b32_e32 v36, v125
	v_mov_b32_e32 v35, v125
	v_mov_b32_e32 v34, v125
	v_mov_b32_e32 v25, v125
	v_mov_b32_e32 v24, v125
	v_mov_b32_e32 v23, v125
	v_mov_b32_e32 v22, v125
	v_mov_b32_e32 v21, v125
	v_mov_b32_e32 v20, v125
	v_mov_b32_e32 v19, v125
	v_mov_b32_e32 v18, v125
	v_mov_b32_e32 v9, v125
	v_mov_b32_e32 v8, v125
	v_mov_b32_e32 v7, v125
	v_mov_b32_e32 v6, v125
	v_mov_b32_e32 v5, v125
	v_mov_b32_e32 v4, v125
	v_mov_b32_e32 v3, v125
	v_mov_b32_e32 v2, v125
	s_cbranch_vccnz .LBB0_299
	s_add_u32 s26, s26, 0x80
	s_addc_u32 s27, s27, 0
	s_add_u32 s40, s28, 0x100
	v_mov_b32_e32 v2, 0
	s_addc_u32 s41, s29, 0
	s_mov_b32 s3, 0
	v_mov_b32_e32 v3, v2
	v_mov_b32_e32 v4, v2
	v_mov_b32_e32 v5, v2
	v_mov_b32_e32 v6, v2
	v_mov_b32_e32 v7, v2
	v_mov_b32_e32 v8, v2
	v_mov_b32_e32 v9, v2
	v_mov_b32_e32 v18, v2
	v_mov_b32_e32 v19, v2
	v_mov_b32_e32 v20, v2
	v_mov_b32_e32 v21, v2
	v_mov_b32_e32 v22, v2
	v_mov_b32_e32 v23, v2
	v_mov_b32_e32 v24, v2
	v_mov_b32_e32 v25, v2
	v_mov_b32_e32 v34, v2
	v_mov_b32_e32 v35, v2
	v_mov_b32_e32 v36, v2
	v_mov_b32_e32 v37, v2
	v_mov_b32_e32 v38, v2
	v_mov_b32_e32 v39, v2
	v_mov_b32_e32 v40, v2
	v_mov_b32_e32 v41, v2
	v_mov_b32_e32 v50, v2
	v_mov_b32_e32 v51, v2
	v_mov_b32_e32 v52, v2
	v_mov_b32_e32 v53, v2
	v_mov_b32_e32 v54, v2
	v_mov_b32_e32 v55, v2
	v_mov_b32_e32 v56, v2
	v_mov_b32_e32 v57, v2
	v_mov_b32_e32 v10, v2
	v_mov_b32_e32 v11, v2
	v_mov_b32_e32 v12, v2
	v_mov_b32_e32 v13, v2
	v_mov_b32_e32 v14, v2
	v_mov_b32_e32 v15, v2
	v_mov_b32_e32 v16, v2
	v_mov_b32_e32 v17, v2
	v_mov_b32_e32 v26, v2
	v_mov_b32_e32 v27, v2
	v_mov_b32_e32 v28, v2
	v_mov_b32_e32 v29, v2
	v_mov_b32_e32 v30, v2
	v_mov_b32_e32 v31, v2
	v_mov_b32_e32 v32, v2
	v_mov_b32_e32 v33, v2
	v_mov_b32_e32 v42, v2
	v_mov_b32_e32 v43, v2
	v_mov_b32_e32 v44, v2
	v_mov_b32_e32 v45, v2
	v_mov_b32_e32 v46, v2
	v_mov_b32_e32 v47, v2
	v_mov_b32_e32 v48, v2
	v_mov_b32_e32 v49, v2
	v_mov_b32_e32 v58, v2
	v_mov_b32_e32 v59, v2
	v_mov_b32_e32 v60, v2
	v_mov_b32_e32 v61, v2
	v_mov_b32_e32 v62, v2
	v_mov_b32_e32 v63, v2
	v_mov_b32_e32 v64, v2
	v_mov_b32_e32 v65, v2
	v_mov_b32_e32 v66, v2
	v_mov_b32_e32 v67, v2
	v_mov_b32_e32 v68, v2
	v_mov_b32_e32 v69, v2
	v_mov_b32_e32 v70, v2
	v_mov_b32_e32 v71, v2
	v_mov_b32_e32 v72, v2
	v_mov_b32_e32 v73, v2
	v_mov_b32_e32 v82, v2
	v_mov_b32_e32 v83, v2
	v_mov_b32_e32 v84, v2
	v_mov_b32_e32 v85, v2
	v_mov_b32_e32 v86, v2
	v_mov_b32_e32 v87, v2
	v_mov_b32_e32 v88, v2
	v_mov_b32_e32 v89, v2
	v_mov_b32_e32 v98, v2
	v_mov_b32_e32 v99, v2
	v_mov_b32_e32 v100, v2
	v_mov_b32_e32 v101, v2
	v_mov_b32_e32 v102, v2
	v_mov_b32_e32 v103, v2
	v_mov_b32_e32 v104, v2
	v_mov_b32_e32 v105, v2
	v_mov_b32_e32 v114, v2
	v_mov_b32_e32 v115, v2
	v_mov_b32_e32 v116, v2
	v_mov_b32_e32 v117, v2
	v_mov_b32_e32 v118, v2
	v_mov_b32_e32 v119, v2
	v_mov_b32_e32 v120, v2
	v_mov_b32_e32 v121, v2
	v_mov_b32_e32 v74, v2
	v_mov_b32_e32 v75, v2
	v_mov_b32_e32 v76, v2
	v_mov_b32_e32 v77, v2
	v_mov_b32_e32 v78, v2
	v_mov_b32_e32 v79, v2
	v_mov_b32_e32 v80, v2
	v_mov_b32_e32 v81, v2
	v_mov_b32_e32 v90, v2
	v_mov_b32_e32 v91, v2
	v_mov_b32_e32 v92, v2
	v_mov_b32_e32 v93, v2
	v_mov_b32_e32 v94, v2
	v_mov_b32_e32 v95, v2
	v_mov_b32_e32 v96, v2
	v_mov_b32_e32 v97, v2
	v_mov_b32_e32 v106, v2
	v_mov_b32_e32 v107, v2
	v_mov_b32_e32 v108, v2
	v_mov_b32_e32 v109, v2
	v_mov_b32_e32 v110, v2
	v_mov_b32_e32 v111, v2
	v_mov_b32_e32 v112, v2
	v_mov_b32_e32 v113, v2
	v_mov_b32_e32 v126, v2
	v_mov_b32_e32 v127, v2
	v_mov_b32_e32 v128, v2
	v_mov_b32_e32 v129, v2
	v_mov_b32_e32 v122, v2
	v_mov_b32_e32 v123, v2
	v_mov_b32_e32 v124, v2
	v_mov_b32_e32 v125, v2
	s_nop 0
	s_nop 0
	s_nop 0

; template <class Epi, class Sched, bool ALIGN_EPI = false, bool SP2 = false, bool GRP = false>
; __device__ __forceinline__ void gemm_phase(PG8_LAS unsigned char* lds, const Gemm g, const Sched& S, const Epi& E) {
;     ...
;         for (int t = 0; t < nt; t += 2) {
;             const bool last = (t == nt - 2);
;             const char* a1 = cA + (size_t)(t + 1) * kstep;
;             const char* a2 = last ? nA : cA + (size_t)(t + 2) * kstep; const char* b2 = last ? nB : cB + (size_t)(t + 2) * kstep;
;             const char* a3 = a2 + kstep; const char* b3 = b2 + kstep;
;     ...
; #pragma unroll
;         for (int a = 0; a < 2; ++a)
; #pragma unroll
;             for (int b = 0; b < 2; ++b)
; #pragma unroll
;                 for (int m = 0; m < 4; ++m)
; #pragma unroll
;                     for (int n = 0; n < 2; ++n) acc[a][b][m][n] = (f32x4){0.f, 0.f, 0.f, 0.f};
;         cur = nxt; cA = nA; cB = nB; ++ui;
.LBB0_408:
	v_mov_b32_e32 v125, 0
	s_andn2_b64 vcc, exec, s[16:17]
	v_mov_b32_e32 v124, v125
	v_mov_b32_e32 v123, v125
	v_mov_b32_e32 v122, v125
	v_mov_b32_e32 v129, v125
	v_mov_b32_e32 v128, v125
	v_mov_b32_e32 v127, v125
	v_mov_b32_e32 v126, v125
	v_mov_b32_e32 v113, v125
	v_mov_b32_e32 v112, v125
	v_mov_b32_e32 v111, v125
	v_mov_b32_e32 v110, v125
	v_mov_b32_e32 v109, v125
	v_mov_b32_e32 v108, v125
	v_mov_b32_e32 v107, v125
	v_mov_b32_e32 v106, v125
	v_mov_b32_e32 v97, v125
	v_mov_b32_e32 v96, v125
	v_mov_b32_e32 v95, v125
	v_mov_b32_e32 v94, v125
	v_mov_b32_e32 v93, v125
	v_mov_b32_e32 v92, v125
	v_mov_b32_e32 v91, v125
	v_mov_b32_e32 v90, v125
	v_mov_b32_e32 v81, v125
	v_mov_b32_e32 v80, v125
	v_mov_b32_e32 v79, v125
	v_mov_b32_e32 v78, v125
	v_mov_b32_e32 v77, v125
	v_mov_b32_e32 v76, v125
	v_mov_b32_e32 v75, v125
	v_mov_b32_e32 v74, v125
	v_mov_b32_e32 v121, v125
	v_mov_b32_e32 v120, v125
	v_mov_b32_e32 v119, v125
	v_mov_b32_e32 v118, v125
	v_mov_b32_e32 v117, v125
	v_mov_b32_e32 v116, v125
	v_mov_b32_e32 v115, v125
	v_mov_b32_e32 v114, v125
	v_mov_b32_e32 v105, v125
	v_mov_b32_e32 v104, v125
	v_mov_b32_e32 v103, v125
	v_mov_b32_e32 v102, v125
	v_mov_b32_e32 v101, v125
	v_mov_b32_e32 v100, v125
	v_mov_b32_e32 v99, v125
	v_mov_b32_e32 v98, v125
	v_mov_b32_e32 v89, v125
	v_mov_b32_e32 v88, v125
	v_mov_b32_e32 v87, v125
	v_mov_b32_e32 v86, v125
	v_mov_b32_e32 v85, v125
	v_mov_b32_e32 v84, v125
	v_mov_b32_e32 v83, v125
	v_mov_b32_e32 v82, v125
	v_mov_b32_e32 v73, v125
	v_mov_b32_e32 v72, v125
	v_mov_b32_e32 v71, v125
	v_mov_b32_e32 v70, v125
	v_mov_b32_e32 v69, v125
	v_mov_b32_e32 v68, v125
	v_mov_b32_e32 v67, v125
	v_mov_b32_e32 v66, v125
	v_mov_b32_e32 v65, v125
	v_mov_b32_e32 v64, v125
	v_mov_b32_e32 v63, v125
	v_mov_b32_e32 v62, v125
	v_mov_b32_e32 v61, v125
	v_mov_b32_e32 v60, v125
	v_mov_b32_e32 v59, v125
	v_mov_b32_e32 v58, v125
	v_mov_b32_e32 v49, v125
	v_mov_b32_e32 v48, v125
	v_mov_b32_e32 v47, v125
	v_mov_b32_e32 v46, v125
	v_mov_b32_e32 v45, v125
	v_mov_b32_e32 v44, v125
	v_mov_b32_e32 v43, v125
	v_mov_b32_e32 v42, v125
	v_mov_b32_e32 v33, v125
	v_mov_b32_e32 v32, v125
	v_mov_b32_e32 v31, v125
	v_mov_b32_e32 v30, v125
	v_mov_b32_e32 v29, v125
	v_mov_b32_e32 v28, v125
	v_mov_b32_e32 v27, v125
	v_mov_b32_e32 v26, v125
	v_mov_b32_e32 v17, v125
	v_mov_b32_e32 v16, v125
	v_mov_b32_e32 v15, v125
	v_mov_b32_e32 v14, v125
	v_mov_b32_e32 v13, v125
	v_mov_b32_e32 v12, v125
	v_mov_b32_e32 v11, v125
	v_mov_b32_e32 v10, v125
	v_mov_b32_e32 v57, v125
	v_mov_b32_e32 v56, v125
	v_mov_b32_e32 v55, v125
	v_mov_b32_e32 v54, v125
	v_mov_b32_e32 v53, v125
	v_mov_b32_e32 v52, v125
	v_mov_b32_e32 v51, v125
	v_mov_b32_e32 v50, v125
	v_mov_b32_e32 v41, v125
	v_mov_b32_e32 v40, v125
	v_mov_b32_e32 v39, v125
	v_mov_b32_e32 v38, v125
	v_mov_b32_e32 v37, v125
	v_mov_b32_e32 v36, v125
	v_mov_b32_e32 v35, v125
	v_mov_b32_e32 v34, v125
	v_mov_b32_e32 v25, v125
	v_mov_b32_e32 v24, v125
	v_mov_b32_e32 v23, v125
	v_mov_b32_e32 v22, v125
	v_mov_b32_e32 v21, v125
	v_mov_b32_e32 v20, v125
	v_mov_b32_e32 v19, v125
	v_mov_b32_e32 v18, v125
	v_mov_b32_e32 v9, v125
	v_mov_b32_e32 v8, v125
	v_mov_b32_e32 v7, v125
	v_mov_b32_e32 v6, v125
	v_mov_b32_e32 v5, v125
	v_mov_b32_e32 v4, v125
	v_mov_b32_e32 v3, v125
	v_mov_b32_e32 v2, v125
	s_cbranch_vccnz .LBB0_411
	s_add_u32 s22, s22, 0x80
	s_addc_u32 s23, s23, 0
	s_add_u32 s40, s26, 0x100
	v_mov_b32_e32 v2, 0
	s_addc_u32 s41, s27, 0
	s_mov_b32 s3, 0
	v_mov_b32_e32 v3, v2
	v_mov_b32_e32 v4, v2
	v_mov_b32_e32 v5, v2
	v_mov_b32_e32 v6, v2
	v_mov_b32_e32 v7, v2
	v_mov_b32_e32 v8, v2
	v_mov_b32_e32 v9, v2
	v_mov_b32_e32 v18, v2
	v_mov_b32_e32 v19, v2
	v_mov_b32_e32 v20, v2
	v_mov_b32_e32 v21, v2
	v_mov_b32_e32 v22, v2
	v_mov_b32_e32 v23, v2
	v_mov_b32_e32 v24, v2
	v_mov_b32_e32 v25, v2
	v_mov_b32_e32 v34, v2
	v_mov_b32_e32 v35, v2
	v_mov_b32_e32 v36, v2
	v_mov_b32_e32 v37, v2
	v_mov_b32_e32 v38, v2
	v_mov_b32_e32 v39, v2
	v_mov_b32_e32 v40, v2
	v_mov_b32_e32 v41, v2
	v_mov_b32_e32 v50, v2
	v_mov_b32_e32 v51, v2
	v_mov_b32_e32 v52, v2
	v_mov_b32_e32 v53, v2
	v_mov_b32_e32 v54, v2
	v_mov_b32_e32 v55, v2
	v_mov_b32_e32 v56, v2
	v_mov_b32_e32 v57, v2
	v_mov_b32_e32 v10, v2
	v_mov_b32_e32 v11, v2
	v_mov_b32_e32 v12, v2
	v_mov_b32_e32 v13, v2
	v_mov_b32_e32 v14, v2
	v_mov_b32_e32 v15, v2
	v_mov_b32_e32 v16, v2
	v_mov_b32_e32 v17, v2
	v_mov_b32_e32 v26, v2
	v_mov_b32_e32 v27, v2
	v_mov_b32_e32 v28, v2
	v_mov_b32_e32 v29, v2
	v_mov_b32_e32 v30, v2
	v_mov_b32_e32 v31, v2
	v_mov_b32_e32 v32, v2
	v_mov_b32_e32 v33, v2
	v_mov_b32_e32 v42, v2
	v_mov_b32_e32 v43, v2
	v_mov_b32_e32 v44, v2
	v_mov_b32_e32 v45, v2
	v_mov_b32_e32 v46, v2
	v_mov_b32_e32 v47, v2
	v_mov_b32_e32 v48, v2
	v_mov_b32_e32 v49, v2
	v_mov_b32_e32 v58, v2
	v_mov_b32_e32 v59, v2
	v_mov_b32_e32 v60, v2
	v_mov_b32_e32 v61, v2
	v_mov_b32_e32 v62, v2
	v_mov_b32_e32 v63, v2
	v_mov_b32_e32 v64, v2
	v_mov_b32_e32 v65, v2
	v_mov_b32_e32 v66, v2
	v_mov_b32_e32 v67, v2
	v_mov_b32_e32 v68, v2
	v_mov_b32_e32 v69, v2
	v_mov_b32_e32 v70, v2
	v_mov_b32_e32 v71, v2
	v_mov_b32_e32 v72, v2
	v_mov_b32_e32 v73, v2
	v_mov_b32_e32 v82, v2
	v_mov_b32_e32 v83, v2
	v_mov_b32_e32 v84, v2
	v_mov_b32_e32 v85, v2
	v_mov_b32_e32 v86, v2
	v_mov_b32_e32 v87, v2
	v_mov_b32_e32 v88, v2
	v_mov_b32_e32 v89, v2
	v_mov_b32_e32 v98, v2
	v_mov_b32_e32 v99, v2
	v_mov_b32_e32 v100, v2
	v_mov_b32_e32 v101, v2
	v_mov_b32_e32 v102, v2
	v_mov_b32_e32 v103, v2
	v_mov_b32_e32 v104, v2
	v_mov_b32_e32 v105, v2
	v_mov_b32_e32 v114, v2
	v_mov_b32_e32 v115, v2
	v_mov_b32_e32 v116, v2
	v_mov_b32_e32 v117, v2
	v_mov_b32_e32 v118, v2
	v_mov_b32_e32 v119, v2
	v_mov_b32_e32 v120, v2
	v_mov_b32_e32 v121, v2
	v_mov_b32_e32 v74, v2
	v_mov_b32_e32 v75, v2
	v_mov_b32_e32 v76, v2
	v_mov_b32_e32 v77, v2
	v_mov_b32_e32 v78, v2
	v_mov_b32_e32 v79, v2
	v_mov_b32_e32 v80, v2
	v_mov_b32_e32 v81, v2
	v_mov_b32_e32 v90, v2
	v_mov_b32_e32 v91, v2
	v_mov_b32_e32 v92, v2
	v_mov_b32_e32 v93, v2
	v_mov_b32_e32 v94, v2
	v_mov_b32_e32 v95, v2
	v_mov_b32_e32 v96, v2
	v_mov_b32_e32 v97, v2
	v_mov_b32_e32 v106, v2
	v_mov_b32_e32 v107, v2
	v_mov_b32_e32 v108, v2
	v_mov_b32_e32 v109, v2
	v_mov_b32_e32 v110, v2
	v_mov_b32_e32 v111, v2
	v_mov_b32_e32 v112, v2
	v_mov_b32_e32 v113, v2
	v_mov_b32_e32 v126, v2
	v_mov_b32_e32 v127, v2
	v_mov_b32_e32 v128, v2
	v_mov_b32_e32 v129, v2
	v_mov_b32_e32 v122, v2
	v_mov_b32_e32 v123, v2
	v_mov_b32_e32 v124, v2
	v_mov_b32_e32 v125, v2
	s_nop 0
	s_nop 0
	s_nop 0
	s_nop 0
	s_nop 0
	s_nop 0
	s_nop 0
	s_nop 0
	s_nop 0
	s_nop 0
	s_nop 0
	s_nop 0

; template <class Epi, class Sched, bool ALIGN_EPI = false, bool SP2 = false, bool GRP = false>
; __device__ __forceinline__ void gemm_phase(PG8_LAS unsigned char* lds, const Gemm g, const Sched& S, const Epi& E) {
;     ...
;         for (int t = 0; t < nt; t += 2) {
;             const bool last = (t == nt - 2);
;             const char* a1 = cA + (size_t)(t + 1) * kstep;
;             const char* a2 = last ? nA : cA + (size_t)(t + 2) * kstep; const char* b2 = last ? nB : cB + (size_t)(t + 2) * kstep;
;             const char* a3 = a2 + kstep; const char* b3 = b2 + kstep;
;     ...
; #pragma unroll
;         for (int a = 0; a < 2; ++a)
; #pragma unroll
;             for (int b = 0; b < 2; ++b)
; #pragma unroll
;                 for (int m = 0; m < 4; ++m)
; #pragma unroll
;                     for (int n = 0; n < 2; ++n) acc[a][b][m][n] = (f32x4){0.f, 0.f, 0.f, 0.f};
;         cur = nxt; cA = nA; cB = nB; ++ui;
.LBB0_522:
	v_mov_b32_e32 v129, 0
	s_andn2_b64 vcc, exec, s[16:17]
	v_mov_b32_e32 v128, v129
	v_mov_b32_e32 v127, v129
	v_mov_b32_e32 v126, v129
	v_mov_b32_e32 v125, v129
	v_mov_b32_e32 v124, v129
	v_mov_b32_e32 v123, v129
	v_mov_b32_e32 v122, v129
	v_mov_b32_e32 v113, v129
	v_mov_b32_e32 v112, v129
	v_mov_b32_e32 v111, v129
	v_mov_b32_e32 v110, v129
	v_mov_b32_e32 v109, v129
	v_mov_b32_e32 v108, v129
	v_mov_b32_e32 v107, v129
	v_mov_b32_e32 v106, v129
	v_mov_b32_e32 v97, v129
	v_mov_b32_e32 v96, v129
	v_mov_b32_e32 v95, v129
	v_mov_b32_e32 v94, v129
	v_mov_b32_e32 v93, v129
	v_mov_b32_e32 v92, v129
	v_mov_b32_e32 v91, v129
	v_mov_b32_e32 v90, v129
	v_mov_b32_e32 v81, v129
	v_mov_b32_e32 v80, v129
	v_mov_b32_e32 v79, v129
	v_mov_b32_e32 v78, v129
	v_mov_b32_e32 v77, v129
	v_mov_b32_e32 v76, v129
	v_mov_b32_e32 v75, v129
	v_mov_b32_e32 v74, v129
	v_mov_b32_e32 v121, v129
	v_mov_b32_e32 v120, v129
	v_mov_b32_e32 v119, v129
	v_mov_b32_e32 v118, v129
	v_mov_b32_e32 v117, v129
	v_mov_b32_e32 v116, v129
	v_mov_b32_e32 v115, v129
	v_mov_b32_e32 v114, v129
	v_mov_b32_e32 v105, v129
	v_mov_b32_e32 v104, v129
	v_mov_b32_e32 v103, v129
	v_mov_b32_e32 v102, v129
	v_mov_b32_e32 v101, v129
	v_mov_b32_e32 v100, v129
	v_mov_b32_e32 v99, v129
	v_mov_b32_e32 v98, v129
	v_mov_b32_e32 v89, v129
	v_mov_b32_e32 v88, v129
	v_mov_b32_e32 v87, v129
	v_mov_b32_e32 v86, v129
	v_mov_b32_e32 v85, v129
	v_mov_b32_e32 v84, v129
	v_mov_b32_e32 v83, v129
	v_mov_b32_e32 v82, v129
	v_mov_b32_e32 v73, v129
	v_mov_b32_e32 v72, v129
	v_mov_b32_e32 v71, v129
	v_mov_b32_e32 v70, v129
	v_mov_b32_e32 v69, v129
	v_mov_b32_e32 v68, v129
	v_mov_b32_e32 v67, v129
	v_mov_b32_e32 v66, v129
	v_mov_b32_e32 v65, v129
	v_mov_b32_e32 v64, v129
	v_mov_b32_e32 v63, v129
	v_mov_b32_e32 v62, v129
	v_mov_b32_e32 v61, v129
	v_mov_b32_e32 v60, v129
	v_mov_b32_e32 v59, v129
	v_mov_b32_e32 v58, v129
	v_mov_b32_e32 v49, v129
	v_mov_b32_e32 v48, v129
	v_mov_b32_e32 v47, v129
	v_mov_b32_e32 v46, v129
	v_mov_b32_e32 v45, v129
	v_mov_b32_e32 v44, v129
	v_mov_b32_e32 v43, v129
	v_mov_b32_e32 v42, v129
	v_mov_b32_e32 v33, v129
	v_mov_b32_e32 v32, v129
	v_mov_b32_e32 v31, v129
	v_mov_b32_e32 v30, v129
	v_mov_b32_e32 v29, v129
	v_mov_b32_e32 v28, v129
	v_mov_b32_e32 v27, v129
	v_mov_b32_e32 v26, v129
	v_mov_b32_e32 v17, v129
	v_mov_b32_e32 v16, v129
	v_mov_b32_e32 v15, v129
	v_mov_b32_e32 v14, v129
	v_mov_b32_e32 v13, v129
	v_mov_b32_e32 v12, v129
	v_mov_b32_e32 v11, v129
	v_mov_b32_e32 v10, v129
	v_mov_b32_e32 v57, v129
	v_mov_b32_e32 v56, v129
	v_mov_b32_e32 v55, v129
	v_mov_b32_e32 v54, v129
	v_mov_b32_e32 v53, v129
	v_mov_b32_e32 v52, v129
	v_mov_b32_e32 v51, v129
	v_mov_b32_e32 v50, v129
	v_mov_b32_e32 v41, v129
	v_mov_b32_e32 v40, v129
	v_mov_b32_e32 v39, v129
	v_mov_b32_e32 v38, v129
	v_mov_b32_e32 v37, v129
	v_mov_b32_e32 v36, v129
	v_mov_b32_e32 v35, v129
	v_mov_b32_e32 v34, v129
	v_mov_b32_e32 v25, v129
	v_mov_b32_e32 v24, v129
	v_mov_b32_e32 v23, v129
	v_mov_b32_e32 v22, v129
	v_mov_b32_e32 v21, v129
	v_mov_b32_e32 v20, v129
	v_mov_b32_e32 v19, v129
	v_mov_b32_e32 v18, v129
	v_mov_b32_e32 v9, v129
	v_mov_b32_e32 v8, v129
	v_mov_b32_e32 v7, v129
	v_mov_b32_e32 v6, v129
	v_mov_b32_e32 v5, v129
	v_mov_b32_e32 v4, v129
	v_mov_b32_e32 v3, v129
	v_mov_b32_e32 v2, v129
	s_cbranch_vccnz .LBB0_526
	s_add_u32 s22, s22, 0x80
	s_addc_u32 s23, s23, 0
	s_add_u32 s39, s26, 0x100
	v_mov_b32_e32 v2, 0
	s_addc_u32 s40, s27, 0
	s_mov_b32 s3, 0
	v_mov_b32_e32 v3, v2
	v_mov_b32_e32 v4, v2
	v_mov_b32_e32 v5, v2
	v_mov_b32_e32 v6, v2
	v_mov_b32_e32 v7, v2
	v_mov_b32_e32 v8, v2
	v_mov_b32_e32 v9, v2
	v_mov_b32_e32 v18, v2
	v_mov_b32_e32 v19, v2
	v_mov_b32_e32 v20, v2
	v_mov_b32_e32 v21, v2
	v_mov_b32_e32 v22, v2
	v_mov_b32_e32 v23, v2
	v_mov_b32_e32 v24, v2
	v_mov_b32_e32 v25, v2
	v_mov_b32_e32 v34, v2
	v_mov_b32_e32 v35, v2
	v_mov_b32_e32 v36, v2
	v_mov_b32_e32 v37, v2
	v_mov_b32_e32 v38, v2
	v_mov_b32_e32 v39, v2
	v_mov_b32_e32 v40, v2
	v_mov_b32_e32 v41, v2
	v_mov_b32_e32 v50, v2
	v_mov_b32_e32 v51, v2
	v_mov_b32_e32 v52, v2
	v_mov_b32_e32 v53, v2
	v_mov_b32_e32 v54, v2
	v_mov_b32_e32 v55, v2
	v_mov_b32_e32 v56, v2
	v_mov_b32_e32 v57, v2
	v_mov_b32_e32 v10, v2
	v_mov_b32_e32 v11, v2
	v_mov_b32_e32 v12, v2
	v_mov_b32_e32 v13, v2
	v_mov_b32_e32 v14, v2
	v_mov_b32_e32 v15, v2
	v_mov_b32_e32 v16, v2
	v_mov_b32_e32 v17, v2
	v_mov_b32_e32 v26, v2
	v_mov_b32_e32 v27, v2
	v_mov_b32_e32 v28, v2
	v_mov_b32_e32 v29, v2
	v_mov_b32_e32 v30, v2
	v_mov_b32_e32 v31, v2
	v_mov_b32_e32 v32, v2
	v_mov_b32_e32 v33, v2
	v_mov_b32_e32 v42, v2
	v_mov_b32_e32 v43, v2
	v_mov_b32_e32 v44, v2
	v_mov_b32_e32 v45, v2
	v_mov_b32_e32 v46, v2
	v_mov_b32_e32 v47, v2
	v_mov_b32_e32 v48, v2
	v_mov_b32_e32 v49, v2
	v_mov_b32_e32 v58, v2
	v_mov_b32_e32 v59, v2
	v_mov_b32_e32 v60, v2
	v_mov_b32_e32 v61, v2
	v_mov_b32_e32 v62, v2
	v_mov_b32_e32 v63, v2
	v_mov_b32_e32 v64, v2
	v_mov_b32_e32 v65, v2
	v_mov_b32_e32 v66, v2
	v_mov_b32_e32 v67, v2
	v_mov_b32_e32 v68, v2
	v_mov_b32_e32 v69, v2
	v_mov_b32_e32 v70, v2
	v_mov_b32_e32 v71, v2
	v_mov_b32_e32 v72, v2
	v_mov_b32_e32 v73, v2
	v_mov_b32_e32 v82, v2
	v_mov_b32_e32 v83, v2
	v_mov_b32_e32 v84, v2
	v_mov_b32_e32 v85, v2
	v_mov_b32_e32 v86, v2
	v_mov_b32_e32 v87, v2
	v_mov_b32_e32 v88, v2
	v_mov_b32_e32 v89, v2
	v_mov_b32_e32 v98, v2
	v_mov_b32_e32 v99, v2
	v_mov_b32_e32 v100, v2
	v_mov_b32_e32 v101, v2
	v_mov_b32_e32 v102, v2
	v_mov_b32_e32 v103, v2
	v_mov_b32_e32 v104, v2
	v_mov_b32_e32 v105, v2
	v_mov_b32_e32 v114, v2
	v_mov_b32_e32 v115, v2
	v_mov_b32_e32 v116, v2
	v_mov_b32_e32 v117, v2
	v_mov_b32_e32 v118, v2
	v_mov_b32_e32 v119, v2
	v_mov_b32_e32 v120, v2
	v_mov_b32_e32 v121, v2
	v_mov_b32_e32 v74, v2
	v_mov_b32_e32 v75, v2
	v_mov_b32_e32 v76, v2
	v_mov_b32_e32 v77, v2
	v_mov_b32_e32 v78, v2
	v_mov_b32_e32 v79, v2
	v_mov_b32_e32 v80, v2
	v_mov_b32_e32 v81, v2
	v_mov_b32_e32 v90, v2
	v_mov_b32_e32 v91, v2
	v_mov_b32_e32 v92, v2
	v_mov_b32_e32 v93, v2
	v_mov_b32_e32 v94, v2
	v_mov_b32_e32 v95, v2
	v_mov_b32_e32 v96, v2
	v_mov_b32_e32 v97, v2
	v_mov_b32_e32 v106, v2
	v_mov_b32_e32 v107, v2
	v_mov_b32_e32 v108, v2
	v_mov_b32_e32 v109, v2
	v_mov_b32_e32 v110, v2
	v_mov_b32_e32 v111, v2
	v_mov_b32_e32 v112, v2
	v_mov_b32_e32 v113, v2
	v_mov_b32_e32 v122, v2
	v_mov_b32_e32 v123, v2
	v_mov_b32_e32 v124, v2
	v_mov_b32_e32 v125, v2
	v_mov_b32_e32 v126, v2
	v_mov_b32_e32 v127, v2
	v_mov_b32_e32 v128, v2
	v_mov_b32_e32 v129, v2
	s_nop 0
	s_nop 0
	s_nop 0
	s_nop 0
	s_nop 0
	s_nop 0
	s_nop 0
	s_nop 0
	s_nop 0
	s_nop 0
	s_nop 0
	s_nop 0
	s_nop 0

; template <class Epi, class Sched, bool ALIGN_EPI = false, bool SP2 = false, bool GRP = false>
; __device__ __forceinline__ void gemm_phase(PG8_LAS unsigned char* lds, const Gemm g, const Sched& S, const Epi& E) {
;     ...
;         for (int t = 0; t < nt; t += 2) {
;             const bool last = (t == nt - 2);
;             const char* a1 = cA + (size_t)(t + 1) * kstep;
;             const char* a2 = last ? nA : cA + (size_t)(t + 2) * kstep; const char* b2 = last ? nB : cB + (size_t)(t + 2) * kstep;
;             const char* a3 = a2 + kstep; const char* b3 = b2 + kstep;
;     ...
; #pragma unroll
;         for (int a = 0; a < 2; ++a)
; #pragma unroll
;             for (int b = 0; b < 2; ++b)
; #pragma unroll
;                 for (int m = 0; m < 4; ++m)
; #pragma unroll
;                     for (int n = 0; n < 2; ++n) acc[a][b][m][n] = (f32x4){0.f, 0.f, 0.f, 0.f};
;         cur = nxt; cA = nA; cB = nB; ++ui;
.LBB0_705:
	v_mov_b32_e32 v129, 0
	s_andn2_b64 vcc, exec, s[22:23]
	v_mov_b32_e32 v128, v129
	v_mov_b32_e32 v127, v129
	v_mov_b32_e32 v126, v129
	v_mov_b32_e32 v125, v129
	v_mov_b32_e32 v124, v129
	v_mov_b32_e32 v123, v129
	v_mov_b32_e32 v122, v129
	v_mov_b32_e32 v113, v129
	v_mov_b32_e32 v112, v129
	v_mov_b32_e32 v111, v129
	v_mov_b32_e32 v110, v129
	v_mov_b32_e32 v109, v129
	v_mov_b32_e32 v108, v129
	v_mov_b32_e32 v107, v129
	v_mov_b32_e32 v106, v129
	v_mov_b32_e32 v97, v129
	v_mov_b32_e32 v96, v129
	v_mov_b32_e32 v95, v129
	v_mov_b32_e32 v94, v129
	v_mov_b32_e32 v93, v129
	v_mov_b32_e32 v92, v129
	v_mov_b32_e32 v91, v129
	v_mov_b32_e32 v90, v129
	v_mov_b32_e32 v81, v129
	v_mov_b32_e32 v80, v129
	v_mov_b32_e32 v79, v129
	v_mov_b32_e32 v78, v129
	v_mov_b32_e32 v77, v129
	v_mov_b32_e32 v76, v129
	v_mov_b32_e32 v75, v129
	v_mov_b32_e32 v74, v129
	v_mov_b32_e32 v121, v129
	v_mov_b32_e32 v120, v129
	v_mov_b32_e32 v119, v129
	v_mov_b32_e32 v118, v129
	v_mov_b32_e32 v117, v129
	v_mov_b32_e32 v116, v129
	v_mov_b32_e32 v115, v129
	v_mov_b32_e32 v114, v129
	v_mov_b32_e32 v105, v129
	v_mov_b32_e32 v104, v129
	v_mov_b32_e32 v103, v129
	v_mov_b32_e32 v102, v129
	v_mov_b32_e32 v101, v129
	v_mov_b32_e32 v100, v129
	v_mov_b32_e32 v99, v129
	v_mov_b32_e32 v98, v129
	v_mov_b32_e32 v89, v129
	v_mov_b32_e32 v88, v129
	v_mov_b32_e32 v87, v129
	v_mov_b32_e32 v86, v129
	v_mov_b32_e32 v85, v129
	v_mov_b32_e32 v84, v129
	v_mov_b32_e32 v83, v129
	v_mov_b32_e32 v82, v129
	v_mov_b32_e32 v73, v129
	v_mov_b32_e32 v72, v129
	v_mov_b32_e32 v71, v129
	v_mov_b32_e32 v70, v129
	v_mov_b32_e32 v69, v129
	v_mov_b32_e32 v68, v129
	v_mov_b32_e32 v67, v129
	v_mov_b32_e32 v66, v129
	v_mov_b32_e32 v65, v129
	v_mov_b32_e32 v64, v129
	v_mov_b32_e32 v63, v129
	v_mov_b32_e32 v62, v129
	v_mov_b32_e32 v61, v129
	v_mov_b32_e32 v60, v129
	v_mov_b32_e32 v59, v129
	v_mov_b32_e32 v58, v129
	v_mov_b32_e32 v49, v129
	v_mov_b32_e32 v48, v129
	v_mov_b32_e32 v47, v129
	v_mov_b32_e32 v46, v129
	v_mov_b32_e32 v45, v129
	v_mov_b32_e32 v44, v129
	v_mov_b32_e32 v43, v129
	v_mov_b32_e32 v42, v129
	v_mov_b32_e32 v33, v129
	v_mov_b32_e32 v32, v129
	v_mov_b32_e32 v31, v129
	v_mov_b32_e32 v30, v129
	v_mov_b32_e32 v29, v129
	v_mov_b32_e32 v28, v129
	v_mov_b32_e32 v27, v129
	v_mov_b32_e32 v26, v129
	v_mov_b32_e32 v17, v129
	v_mov_b32_e32 v16, v129
	v_mov_b32_e32 v15, v129
	v_mov_b32_e32 v14, v129
	v_mov_b32_e32 v13, v129
	v_mov_b32_e32 v12, v129
	v_mov_b32_e32 v11, v129
	v_mov_b32_e32 v10, v129
	v_mov_b32_e32 v57, v129
	v_mov_b32_e32 v56, v129
	v_mov_b32_e32 v55, v129
	v_mov_b32_e32 v54, v129
	v_mov_b32_e32 v53, v129
	v_mov_b32_e32 v52, v129
	v_mov_b32_e32 v51, v129
	v_mov_b32_e32 v50, v129
	v_mov_b32_e32 v41, v129
	v_mov_b32_e32 v40, v129
	v_mov_b32_e32 v39, v129
	v_mov_b32_e32 v38, v129
	v_mov_b32_e32 v37, v129
	v_mov_b32_e32 v36, v129
	v_mov_b32_e32 v35, v129
	v_mov_b32_e32 v34, v129
	v_mov_b32_e32 v25, v129
	v_mov_b32_e32 v24, v129
	v_mov_b32_e32 v23, v129
	v_mov_b32_e32 v22, v129
	v_mov_b32_e32 v21, v129
	v_mov_b32_e32 v20, v129
	v_mov_b32_e32 v19, v129
	v_mov_b32_e32 v18, v129
	v_mov_b32_e32 v9, v129
	v_mov_b32_e32 v8, v129
	v_mov_b32_e32 v7, v129
	v_mov_b32_e32 v6, v129
	v_mov_b32_e32 v5, v129
	v_mov_b32_e32 v4, v129
	v_mov_b32_e32 v3, v129
	v_mov_b32_e32 v2, v129
	s_cbranch_vccnz .LBB0_708
	s_add_u32 s70, s70, 0x80
	s_addc_u32 s71, s71, 0
	s_add_u32 s25, s72, 0x100
	v_mov_b32_e32 v2, 0
	s_addc_u32 s33, s73, 0
	s_mov_b32 s3, 0
	v_mov_b32_e32 v3, v2
	v_mov_b32_e32 v4, v2
	v_mov_b32_e32 v5, v2
	v_mov_b32_e32 v6, v2
	v_mov_b32_e32 v7, v2
	v_mov_b32_e32 v8, v2
	v_mov_b32_e32 v9, v2
	v_mov_b32_e32 v18, v2
	v_mov_b32_e32 v19, v2
	v_mov_b32_e32 v20, v2
	v_mov_b32_e32 v21, v2
	v_mov_b32_e32 v22, v2
	v_mov_b32_e32 v23, v2
	v_mov_b32_e32 v24, v2
	v_mov_b32_e32 v25, v2
	v_mov_b32_e32 v34, v2
	v_mov_b32_e32 v35, v2
	v_mov_b32_e32 v36, v2
	v_mov_b32_e32 v37, v2
	v_mov_b32_e32 v38, v2
	v_mov_b32_e32 v39, v2
	v_mov_b32_e32 v40, v2
	v_mov_b32_e32 v41, v2
	v_mov_b32_e32 v50, v2
	v_mov_b32_e32 v51, v2
	v_mov_b32_e32 v52, v2
	v_mov_b32_e32 v53, v2
	v_mov_b32_e32 v54, v2
	v_mov_b32_e32 v55, v2
	v_mov_b32_e32 v56, v2
	v_mov_b32_e32 v57, v2
	v_mov_b32_e32 v10, v2
	v_mov_b32_e32 v11, v2
	v_mov_b32_e32 v12, v2
	v_mov_b32_e32 v13, v2
	v_mov_b32_e32 v14, v2
	v_mov_b32_e32 v15, v2
	v_mov_b32_e32 v16, v2
	v_mov_b32_e32 v17, v2
	v_mov_b32_e32 v26, v2
	v_mov_b32_e32 v27, v2
	v_mov_b32_e32 v28, v2
	v_mov_b32_e32 v29, v2
	v_mov_b32_e32 v30, v2
	v_mov_b32_e32 v31, v2
	v_mov_b32_e32 v32, v2
	v_mov_b32_e32 v33, v2
	v_mov_b32_e32 v42, v2
	v_mov_b32_e32 v43, v2
	v_mov_b32_e32 v44, v2
	v_mov_b32_e32 v45, v2
	v_mov_b32_e32 v46, v2
	v_mov_b32_e32 v47, v2
	v_mov_b32_e32 v48, v2
	v_mov_b32_e32 v49, v2
	v_mov_b32_e32 v58, v2
	v_mov_b32_e32 v59, v2
	v_mov_b32_e32 v60, v2
	v_mov_b32_e32 v61, v2
	v_mov_b32_e32 v62, v2
	v_mov_b32_e32 v63, v2
	v_mov_b32_e32 v64, v2
	v_mov_b32_e32 v65, v2
	v_mov_b32_e32 v66, v2
	v_mov_b32_e32 v67, v2
	v_mov_b32_e32 v68, v2
	v_mov_b32_e32 v69, v2
	v_mov_b32_e32 v70, v2
	v_mov_b32_e32 v71, v2
	v_mov_b32_e32 v72, v2
	v_mov_b32_e32 v73, v2
	v_mov_b32_e32 v82, v2
	v_mov_b32_e32 v83, v2
	v_mov_b32_e32 v84, v2
	v_mov_b32_e32 v85, v2
	v_mov_b32_e32 v86, v2
	v_mov_b32_e32 v87, v2
	v_mov_b32_e32 v88, v2
	v_mov_b32_e32 v89, v2
	v_mov_b32_e32 v98, v2
	v_mov_b32_e32 v99, v2
	v_mov_b32_e32 v100, v2
	v_mov_b32_e32 v101, v2
	v_mov_b32_e32 v102, v2
	v_mov_b32_e32 v103, v2
	v_mov_b32_e32 v104, v2
	v_mov_b32_e32 v105, v2
	v_mov_b32_e32 v114, v2
	v_mov_b32_e32 v115, v2
	v_mov_b32_e32 v116, v2
	v_mov_b32_e32 v117, v2
	v_mov_b32_e32 v118, v2
	v_mov_b32_e32 v119, v2
	v_mov_b32_e32 v120, v2
	v_mov_b32_e32 v121, v2
	v_mov_b32_e32 v74, v2
	v_mov_b32_e32 v75, v2
	v_mov_b32_e32 v76, v2
	v_mov_b32_e32 v77, v2
	v_mov_b32_e32 v78, v2
	v_mov_b32_e32 v79, v2
	v_mov_b32_e32 v80, v2
	v_mov_b32_e32 v81, v2
	v_mov_b32_e32 v90, v2
	v_mov_b32_e32 v91, v2
	v_mov_b32_e32 v92, v2
	v_mov_b32_e32 v93, v2
	v_mov_b32_e32 v94, v2
	v_mov_b32_e32 v95, v2
	v_mov_b32_e32 v96, v2
	v_mov_b32_e32 v97, v2
	v_mov_b32_e32 v106, v2
	v_mov_b32_e32 v107, v2
	v_mov_b32_e32 v108, v2
	v_mov_b32_e32 v109, v2
	v_mov_b32_e32 v110, v2
	v_mov_b32_e32 v111, v2
	v_mov_b32_e32 v112, v2
	v_mov_b32_e32 v113, v2
	v_mov_b32_e32 v122, v2
	v_mov_b32_e32 v123, v2
	v_mov_b32_e32 v124, v2
	v_mov_b32_e32 v125, v2
	v_mov_b32_e32 v126, v2
	v_mov_b32_e32 v127, v2
	v_mov_b32_e32 v128, v2
	v_mov_b32_e32 v129, v2
	s_nop 0
	s_nop 0
	s_nop 0
	s_nop 0
	s_nop 0
	s_nop 0
	s_nop 0
	s_nop 0
	s_nop 0

; template <class Epi, class Sched, bool ALIGN_EPI = false, bool SP2 = false, bool GRP = false>
; __device__ __forceinline__ void gemm_phase(PG8_LAS unsigned char* lds, const Gemm g, const Sched& S, const Epi& E) {
;     ...
;         for (int t = 0; t < nt; t += 2) {
;             const bool last = (t == nt - 2);
;             const char* a1 = cA + (size_t)(t + 1) * kstep;
;             const char* a2 = last ? nA : cA + (size_t)(t + 2) * kstep; const char* b2 = last ? nB : cB + (size_t)(t + 2) * kstep;
;             const char* a3 = a2 + kstep; const char* b3 = b2 + kstep;
.LBB0_885:
	s_add_u32 s82, s76, 0x80
	s_addc_u32 s83, s77, 0
	s_add_u32 s55, s74, 0x100
	s_addc_u32 s96, s75, 0
	s_mov_b32 s84, 0
	s_nop 0
	s_nop 0
	s_nop 0

; template <class Epi, class Sched, bool ALIGN_EPI = false, bool SP2 = false, bool GRP = false>
; __device__ __forceinline__ void gemm_phase(PG8_LAS unsigned char* lds, const Gemm g, const Sched& S, const Epi& E) {
;     ...
;         for (int t = 0; t < nt; t += 2) {
;             const bool last = (t == nt - 2);
;             const char* a1 = cA + (size_t)(t + 1) * kstep;
;             const char* a2 = last ? nA : cA + (size_t)(t + 2) * kstep; const char* b2 = last ? nB : cB + (size_t)(t + 2) * kstep;
;             const char* a3 = a2 + kstep; const char* b3 = b2 + kstep;
.LBB0_1104:
	s_add_u32 s82, s76, 0x80
	s_addc_u32 s83, s77, 0
	s_add_u32 vcc_lo, s74, 0x100
	s_addc_u32 vcc_hi, s75, 0
	s_mov_b32 s84, 0
	s_nop 0
	s_nop 0
	s_nop 0
	s_nop 0
	s_nop 0
	s_nop 0
	s_nop 0
	s_nop 0
	s_nop 0
	s_nop 0
	s_nop 0
	s_nop 0

; template <class Epi, class Sched, bool ALIGN_EPI = false, bool SP2 = false, bool GRP = false>
; __device__ __forceinline__ void gemm_phase(PG8_LAS unsigned char* lds, const Gemm g, const Sched& S, const Epi& E) {
;     ...
;         for (int t = 0; t < nt; t += 2) {
;             const bool last = (t == nt - 2);
;             const char* a1 = cA + (size_t)(t + 1) * kstep;
;             const char* a2 = last ? nA : cA + (size_t)(t + 2) * kstep; const char* b2 = last ? nB : cB + (size_t)(t + 2) * kstep;
;             const char* a3 = a2 + kstep; const char* b3 = b2 + kstep;
.LBB0_1189:
	s_add_u32 s82, s76, 0x80
	s_addc_u32 s83, s77, 0
	s_add_u32 vcc_lo, s74, 0x100
	s_addc_u32 vcc_hi, s75, 0
	s_mov_b32 s84, 0
	s_nop 0
	s_nop 0
	s_nop 0
